# experiment: write-through (sc1) epilogue stores for the single-round GEMMs P4 and P7
# baseline (speedup 1.0000x reference)
.LBB0_991:
	v_lshl_add_u32 v152, s28, 8, v1
	v_lshl_or_b32 v154, s54, 8, v147
	v_ashrrev_i32_e32 v153, 31, v152
	v_ashrrev_i32_e32 v155, 31, v154
	v_cvt_pk_bf16_f32 v126, v126, v127
	v_cvt_pk_bf16_f32 v127, v128, v129
	v_cvt_pk_bf16_f32 v128, v122, v123
	v_lshlrev_b64 v[122:123], 12, v[152:153]
	v_cvt_pk_bf16_f32 v129, v124, v125
	v_lshl_add_u64 v[122:123], s[4:5], 0, v[122:123]
	v_lshlrev_b64 v[124:125], 1, v[154:155]
	v_lshl_add_u64 v[122:123], v[122:123], 0, v[124:125]
	global_store_dwordx4 v[122:123], v[126:129], off sc1
	v_cvt_pk_bf16_f32 v114, v114, v115
	v_cvt_pk_bf16_f32 v115, v116, v117
	v_cvt_pk_bf16_f32 v116, v106, v107
	v_cvt_pk_bf16_f32 v117, v108, v109
	global_store_dwordx4 v[122:123], v[114:117], off offset:256 sc1
	v_cvt_pk_bf16_f32 v106, v118, v119
	v_cvt_pk_bf16_f32 v107, v120, v121
	v_cvt_pk_bf16_f32 v108, v110, v111
	v_cvt_pk_bf16_f32 v109, v112, v113
	s_nop 1
	v_or_b32_e32 v114, 16, v152
	v_ashrrev_i32_e32 v115, 31, v114
	v_lshlrev_b64 v[110:111], 12, v[114:115]
	v_lshl_add_u64 v[110:111], s[4:5], 0, v[110:111]
	v_lshl_add_u64 v[110:111], v[110:111], 0, v[124:125]
	global_store_dwordx4 v[110:111], v[106:109], off sc1
	v_cvt_pk_bf16_f32 v98, v98, v99
	v_cvt_pk_bf16_f32 v99, v100, v101
	v_cvt_pk_bf16_f32 v100, v90, v91
	v_cvt_pk_bf16_f32 v101, v92, v93
	global_store_dwordx4 v[110:111], v[98:101], off offset:256 sc1
	v_cvt_pk_bf16_f32 v90, v102, v103
	v_cvt_pk_bf16_f32 v91, v104, v105
	v_cvt_pk_bf16_f32 v92, v94, v95
	v_cvt_pk_bf16_f32 v93, v96, v97
	s_nop 1
	v_or_b32_e32 v98, 32, v152
	v_ashrrev_i32_e32 v99, 31, v98
	v_lshlrev_b64 v[94:95], 12, v[98:99]
	v_lshl_add_u64 v[94:95], s[4:5], 0, v[94:95]
	v_lshl_add_u64 v[94:95], v[94:95], 0, v[124:125]
	global_store_dwordx4 v[94:95], v[90:93], off sc1
	v_cvt_pk_bf16_f32 v82, v82, v83
	v_cvt_pk_bf16_f32 v83, v84, v85
	v_cvt_pk_bf16_f32 v84, v74, v75
	v_cvt_pk_bf16_f32 v85, v76, v77
	global_store_dwordx4 v[94:95], v[82:85], off offset:256 sc1
	v_cvt_pk_bf16_f32 v74, v86, v87
	v_cvt_pk_bf16_f32 v75, v88, v89
	v_cvt_pk_bf16_f32 v76, v78, v79
	v_cvt_pk_bf16_f32 v77, v80, v81
	s_nop 1
	v_or_b32_e32 v82, 48, v152
	v_ashrrev_i32_e32 v83, 31, v82
	v_lshlrev_b64 v[78:79], 12, v[82:83]
	v_lshl_add_u64 v[78:79], s[4:5], 0, v[78:79]
	v_lshl_add_u64 v[78:79], v[78:79], 0, v[124:125]
	global_store_dwordx4 v[78:79], v[74:77], off sc1
	v_cvt_pk_bf16_f32 v70, v70, v71
	v_cvt_pk_bf16_f32 v71, v72, v73
	v_cvt_pk_bf16_f32 v72, v66, v67
	v_cvt_pk_bf16_f32 v73, v68, v69
	global_store_dwordx4 v[78:79], v[70:73], off offset:256 sc1
	v_cvt_pk_bf16_f32 v62, v62, v63
	v_cvt_pk_bf16_f32 v63, v64, v65
	v_cvt_pk_bf16_f32 v64, v58, v59
	v_cvt_pk_bf16_f32 v65, v60, v61
	v_add_co_u32_e32 v60, vcc, s50, v122
	v_lshl_add_u64 v[58:59], v[122:123], 0, s[6:7]
	s_nop 0
	v_addc_co_u32_e32 v61, vcc, 0, v123, vcc
	global_store_dwordx4 v[60:61], v[62:65], off sc1
	v_cvt_pk_bf16_f32 v50, v50, v51
	v_cvt_pk_bf16_f32 v51, v52, v53
	v_cvt_pk_bf16_f32 v52, v42, v43
	v_cvt_pk_bf16_f32 v53, v44, v45
	global_store_dwordx4 v[58:59], v[50:53], off offset:256 sc1
	v_cvt_pk_bf16_f32 v42, v54, v55
	v_cvt_pk_bf16_f32 v43, v56, v57
	v_cvt_pk_bf16_f32 v44, v46, v47
	v_cvt_pk_bf16_f32 v45, v48, v49
	v_add_co_u32_e32 v48, vcc, s51, v122
	v_lshl_add_u64 v[46:47], v[122:123], 0, s[14:15]
	s_nop 0
	v_addc_co_u32_e32 v49, vcc, 0, v123, vcc
	global_store_dwordx4 v[48:49], v[42:45], off sc1
	v_cvt_pk_bf16_f32 v34, v34, v35
	v_cvt_pk_bf16_f32 v35, v36, v37
	v_cvt_pk_bf16_f32 v36, v26, v27
	v_cvt_pk_bf16_f32 v37, v28, v29
	global_store_dwordx4 v[46:47], v[34:37], off offset:256 sc1
	v_cvt_pk_bf16_f32 v26, v38, v39
	v_cvt_pk_bf16_f32 v27, v40, v41
	v_cvt_pk_bf16_f32 v28, v30, v31
	v_cvt_pk_bf16_f32 v29, v32, v33
	v_add_co_u32_e32 v32, vcc, s52, v122
	v_lshl_add_u64 v[30:31], v[122:123], 0, s[16:17]
	s_nop 0
	v_addc_co_u32_e32 v33, vcc, 0, v123, vcc
	global_store_dwordx4 v[32:33], v[26:29], off sc1
	v_cvt_pk_bf16_f32 v18, v18, v19
	v_cvt_pk_bf16_f32 v19, v20, v21
	v_cvt_pk_bf16_f32 v20, v10, v11
	v_cvt_pk_bf16_f32 v21, v12, v13
	global_store_dwordx4 v[30:31], v[18:21], off offset:256 sc1
	v_cvt_pk_bf16_f32 v10, v22, v23
	v_cvt_pk_bf16_f32 v11, v24, v25
	v_cvt_pk_bf16_f32 v12, v14, v15
	v_cvt_pk_bf16_f32 v13, v16, v17
	v_add_co_u32_e32 v16, vcc, s53, v122
	v_lshl_add_u64 v[14:15], v[122:123], 0, s[18:19]
	s_nop 0
	v_addc_co_u32_e32 v17, vcc, 0, v123, vcc
	s_andn2_b64 vcc, exec, s[0:1]
	s_mov_b64 s[0:1], -1
	global_store_dwordx4 v[16:17], v[10:13], off sc1
	v_cvt_pk_bf16_f32 v6, v6, v7
	v_cvt_pk_bf16_f32 v7, v8, v9
	v_cvt_pk_bf16_f32 v8, v2, v3
	v_cvt_pk_bf16_f32 v9, v4, v5
	global_store_dwordx4 v[14:15], v[6:9], off offset:256 sc1
	s_cbranch_vccnz .LBB0_980
	s_andn2_b64 vcc, exec, s[8:9]
	s_cbranch_vccnz .LBB0_979
	s_barrier
	s_branch .LBB0_979

.LBB0_1225:
	v_lshl_add_u32 v152, s51, 8, v1
	v_lshl_or_b32 v154, s52, 8, v147
	v_ashrrev_i32_e32 v153, 31, v152
	v_ashrrev_i32_e32 v155, 31, v154
	v_cvt_pk_bf16_f32 v126, v126, v127
	v_cvt_pk_bf16_f32 v127, v128, v129
	v_cvt_pk_bf16_f32 v128, v122, v123
	v_lshlrev_b64 v[122:123], 12, v[152:153]
	v_cvt_pk_bf16_f32 v129, v124, v125
	v_lshl_add_u64 v[122:123], s[8:9], 0, v[122:123]
	v_lshlrev_b64 v[124:125], 1, v[154:155]
	v_lshl_add_u64 v[122:123], v[122:123], 0, v[124:125]
	global_store_dwordx4 v[122:123], v[126:129], off sc1
	v_cvt_pk_bf16_f32 v114, v114, v115
	v_cvt_pk_bf16_f32 v115, v116, v117
	v_cvt_pk_bf16_f32 v116, v106, v107
	v_cvt_pk_bf16_f32 v117, v108, v109
	global_store_dwordx4 v[122:123], v[114:117], off offset:256 sc1
	v_cvt_pk_bf16_f32 v106, v118, v119
	v_cvt_pk_bf16_f32 v107, v120, v121
	v_cvt_pk_bf16_f32 v108, v110, v111
	v_cvt_pk_bf16_f32 v109, v112, v113
	v_readlane_b32 s52, v254, 11
	s_nop 0
	v_or_b32_e32 v114, 16, v152
	v_ashrrev_i32_e32 v115, 31, v114
	v_lshlrev_b64 v[110:111], 12, v[114:115]
	v_lshl_add_u64 v[110:111], s[8:9], 0, v[110:111]
	v_lshl_add_u64 v[110:111], v[110:111], 0, v[124:125]
	global_store_dwordx4 v[110:111], v[106:109], off sc1
	v_cvt_pk_bf16_f32 v98, v98, v99
	v_cvt_pk_bf16_f32 v99, v100, v101
	v_cvt_pk_bf16_f32 v100, v90, v91
	v_cvt_pk_bf16_f32 v101, v92, v93
	global_store_dwordx4 v[110:111], v[98:101], off offset:256 sc1
	v_cvt_pk_bf16_f32 v90, v102, v103
	v_cvt_pk_bf16_f32 v91, v104, v105
	v_cvt_pk_bf16_f32 v92, v94, v95
	v_cvt_pk_bf16_f32 v93, v96, v97
	v_readlane_b32 s54, v254, 13
	s_nop 0
	v_or_b32_e32 v98, 32, v152
	v_ashrrev_i32_e32 v99, 31, v98
	v_lshlrev_b64 v[94:95], 12, v[98:99]
	v_lshl_add_u64 v[94:95], s[8:9], 0, v[94:95]
	v_lshl_add_u64 v[94:95], v[94:95], 0, v[124:125]
	global_store_dwordx4 v[94:95], v[90:93], off sc1
	v_cvt_pk_bf16_f32 v82, v82, v83
	v_cvt_pk_bf16_f32 v83, v84, v85
	v_cvt_pk_bf16_f32 v84, v74, v75
	v_cvt_pk_bf16_f32 v85, v76, v77
	global_store_dwordx4 v[94:95], v[82:85], off offset:256 sc1
	v_cvt_pk_bf16_f32 v74, v86, v87
	v_cvt_pk_bf16_f32 v75, v88, v89
	v_cvt_pk_bf16_f32 v76, v78, v79
	v_cvt_pk_bf16_f32 v77, v80, v81
	v_readlane_b32 s55, v254, 14
	s_nop 0
	v_or_b32_e32 v82, 48, v152
	v_ashrrev_i32_e32 v83, 31, v82
	v_lshlrev_b64 v[78:79], 12, v[82:83]
	v_lshl_add_u64 v[78:79], s[8:9], 0, v[78:79]
	v_lshl_add_u64 v[78:79], v[78:79], 0, v[124:125]
	global_store_dwordx4 v[78:79], v[74:77], off sc1
	v_cvt_pk_bf16_f32 v70, v70, v71
	v_cvt_pk_bf16_f32 v71, v72, v73
	v_cvt_pk_bf16_f32 v72, v66, v67
	v_cvt_pk_bf16_f32 v73, v68, v69
	global_store_dwordx4 v[78:79], v[70:73], off offset:256 sc1
	v_cvt_pk_bf16_f32 v62, v62, v63
	v_cvt_pk_bf16_f32 v63, v64, v65
	v_cvt_pk_bf16_f32 v64, v58, v59
	v_cvt_pk_bf16_f32 v65, v60, v61
	v_add_co_u32_e32 v60, vcc, s45, v122
	v_lshl_add_u64 v[58:59], v[122:123], 0, s[14:15]
	s_nop 0
	v_addc_co_u32_e32 v61, vcc, 0, v123, vcc
	global_store_dwordx4 v[60:61], v[62:65], off sc1
	v_cvt_pk_bf16_f32 v50, v50, v51
	v_cvt_pk_bf16_f32 v51, v52, v53
	v_cvt_pk_bf16_f32 v52, v42, v43
	v_cvt_pk_bf16_f32 v53, v44, v45
	global_store_dwordx4 v[58:59], v[50:53], off offset:256 sc1
	v_cvt_pk_bf16_f32 v42, v54, v55
	v_cvt_pk_bf16_f32 v43, v56, v57
	v_cvt_pk_bf16_f32 v44, v46, v47
	v_cvt_pk_bf16_f32 v45, v48, v49
	v_add_co_u32_e32 v48, vcc, s46, v122
	v_lshl_add_u64 v[46:47], v[122:123], 0, s[16:17]
	s_nop 0
	v_addc_co_u32_e32 v49, vcc, 0, v123, vcc
	global_store_dwordx4 v[48:49], v[42:45], off sc1
	v_cvt_pk_bf16_f32 v34, v34, v35
	v_cvt_pk_bf16_f32 v35, v36, v37
	v_cvt_pk_bf16_f32 v36, v26, v27
	v_cvt_pk_bf16_f32 v37, v28, v29
	global_store_dwordx4 v[46:47], v[34:37], off offset:256 sc1
	v_cvt_pk_bf16_f32 v26, v38, v39
	v_cvt_pk_bf16_f32 v27, v40, v41
	v_cvt_pk_bf16_f32 v28, v30, v31
	v_cvt_pk_bf16_f32 v29, v32, v33
	v_add_co_u32_e32 v32, vcc, s47, v122
	v_lshl_add_u64 v[30:31], v[122:123], 0, s[18:19]
	s_nop 0
	v_addc_co_u32_e32 v33, vcc, 0, v123, vcc
	global_store_dwordx4 v[32:33], v[26:29], off sc1
	v_cvt_pk_bf16_f32 v18, v18, v19
	v_cvt_pk_bf16_f32 v19, v20, v21
	v_cvt_pk_bf16_f32 v20, v10, v11
	v_cvt_pk_bf16_f32 v21, v12, v13
	global_store_dwordx4 v[30:31], v[18:21], off offset:256 sc1
	v_cvt_pk_bf16_f32 v10, v22, v23
	v_cvt_pk_bf16_f32 v11, v24, v25
	v_cvt_pk_bf16_f32 v12, v14, v15
	v_cvt_pk_bf16_f32 v13, v16, v17
	v_add_co_u32_e32 v16, vcc, s48, v122
	v_readlane_b32 s58, v254, 17
	s_nop 0
	v_addc_co_u32_e32 v17, vcc, 0, v123, vcc
	v_readlane_b32 s59, v254, 18
	v_lshl_add_u64 v[14:15], v[122:123], 0, s[20:21]
	s_and_b64 vcc, exec, s[0:1]
	s_mov_b64 s[0:1], -1
	s_mov_b64 s[54:55], s[58:59]
	global_store_dwordx4 v[16:17], v[10:13], off sc1
	v_cvt_pk_bf16_f32 v6, v6, v7
	v_cvt_pk_bf16_f32 v7, v8, v9
	v_cvt_pk_bf16_f32 v8, v2, v3
	v_cvt_pk_bf16_f32 v9, v4, v5
	global_store_dwordx4 v[14:15], v[6:9], off offset:256 sc1
	v_readlane_b32 s53, v254, 12
	v_readlane_b32 s56, v254, 15
	v_readlane_b32 s57, v254, 16
	v_readlane_b32 s60, v254, 19
	v_readlane_b32 s61, v254, 20
	v_readlane_b32 s62, v254, 21
	v_readlane_b32 s63, v254, 22
	v_readlane_b32 s64, v254, 23
	v_readlane_b32 s65, v254, 24
	v_readlane_b32 s66, v254, 25
	v_readlane_b32 s67, v254, 26
	s_cbranch_vccnz .LBB0_1210
	s_andn2_b64 vcc, exec, s[6:7]
	s_cbranch_vccnz .LBB0_1209
	s_barrier
	s_branch .LBB0_1209
